# winb: P1 part2 WINB loop - 32 adaLN scale loads hoisted to loop top, per-substep vmcnt waits removed (stores pipelined)
# baseline (speedup 1.0000x reference)
.LBB0_148:
	s_or_b64 exec, exec, s[34:35]
	v_add_co_u32_e32 v54, vcc, s49, v54
	s_add_i32 s16, s16, s12
	s_nop 0
	v_addc_co_u32_e32 v55, vcc, 0, v55, vcc
	s_add_i32 s34, s20, s16
	s_add_u32 s0, s0, s10
	s_addc_u32 s1, s1, s11
	s_cmpk_gt_i32 s34, 0x7ff
	v_lshl_add_u64 v[52:53], v[52:53], 0, s[22:23]
	v_pk_add_f32 v[72:73], v[220:221], 1.0 op_sel_hi:[1,0]
	v_pk_add_f32 v[78:79], v[226:227], 1.0 op_sel_hi:[1,0]
	v_pk_add_f32 v[76:77], v[224:225], 1.0 op_sel_hi:[1,0]
	v_pk_add_f32 v[74:75], v[222:223], 1.0 op_sel_hi:[1,0]
	v_pk_mul_f32 v[22:23], v[22:23], v[72:73]
	v_pk_mul_f32 v[20:21], v[20:21], v[78:79]
	v_pk_mul_f32 v[18:19], v[18:19], v[76:77]
	v_pk_mul_f32 v[24:25], v[24:25], v[74:75]
	v_pk_mul_f32 v[22:23], v[22:23], v[56:57]
	v_pk_mul_f32 v[56:57], v[20:21], v[62:63]
	v_pk_mul_f32 v[20:21], v[18:19], v[58:59]
	v_pk_mul_f32 v[24:25], v[24:25], v[60:61]
	v_cvt_pk_bf16_f32 v18, v22, v23
	s_nop 0
	v_cvt_pk_bf16_f32 v19, v24, v25
	v_cvt_pk_bf16_f32 v20, v20, v21
	v_cvt_pk_bf16_f32 v21, v56, v57
	global_store_dwordx4 v[54:55], v[18:21], off
	s_nop 1
	s_nop 0
	v_pk_add_f32 v[20:21], v[230:231], 1.0 op_sel_hi:[1,0]
	v_pk_add_f32 v[24:25], v[234:235], 1.0 op_sel_hi:[1,0]
	v_pk_add_f32 v[22:23], v[232:233], 1.0 op_sel_hi:[1,0]
	v_pk_add_f32 v[18:19], v[228:229], 1.0 op_sel_hi:[1,0]
	v_pk_mul_f32 v[12:13], v[12:13], v[24:25]
	v_pk_mul_f32 v[10:11], v[10:11], v[22:23]
	v_pk_mul_f32 v[16:17], v[16:17], v[20:21]
	v_pk_mul_f32 v[14:15], v[14:15], v[18:19]
	v_pk_mul_f32 v[18:19], v[12:13], v[32:33]
	v_pk_mul_f32 v[12:13], v[10:11], v[30:31]
	v_pk_mul_f32 v[16:17], v[16:17], v[28:29]
	v_pk_mul_f32 v[14:15], v[14:15], v[26:27]
	s_nop 0
	v_cvt_pk_bf16_f32 v10, v14, v15
	v_cvt_pk_bf16_f32 v11, v16, v17
	v_cvt_pk_bf16_f32 v12, v12, v13
	v_cvt_pk_bf16_f32 v13, v18, v19
	global_store_dwordx4 v[54:55], v[10:13], off offset:1024
	s_nop 1
	s_cbranch_scc1 .LBB0_169

.LBB0_153:
	global_load_dwordx4 v[18:21], v[34:35], off offset:16
	global_load_dwordx4 v[22:25], v[34:35], off
	s_nop 0
	global_load_dwordx4 v[10:13], v[34:35], off offset:2064
	global_load_dwordx4 v[14:17], v[34:35], off offset:2048
	global_load_dwordx4 v[108:111], v[36:37], off
	global_load_dwordx4 v[112:115], v[36:37], off offset:16
	global_load_dwordx4 v[116:119], v[36:37], off offset:2048
	global_load_dwordx4 v[120:123], v[36:37], off offset:2064
	global_load_dwordx4 v[124:127], v[38:39], off
	global_load_dwordx4 v[128:131], v[38:39], off offset:16
	global_load_dwordx4 v[132:135], v[38:39], off offset:2048
	global_load_dwordx4 v[136:139], v[38:39], off offset:2064
	global_load_dwordx4 v[140:143], v[40:41], off
	global_load_dwordx4 v[144:147], v[40:41], off offset:16
	global_load_dwordx4 v[148:151], v[40:41], off offset:2048
	global_load_dwordx4 v[152:155], v[40:41], off offset:2064
	global_load_dwordx4 v[156:159], v[42:43], off
	global_load_dwordx4 v[160:163], v[42:43], off offset:16
	global_load_dwordx4 v[164:167], v[42:43], off offset:2048
	global_load_dwordx4 v[168:171], v[42:43], off offset:2064
	global_load_dwordx4 v[172:175], v[44:45], off
	global_load_dwordx4 v[176:179], v[44:45], off offset:16
	global_load_dwordx4 v[180:183], v[44:45], off offset:2048
	global_load_dwordx4 v[184:187], v[44:45], off offset:2064
	global_load_dwordx4 v[188:191], v[46:47], off
	global_load_dwordx4 v[192:195], v[46:47], off offset:16
	global_load_dwordx4 v[196:199], v[46:47], off offset:2048
	global_load_dwordx4 v[200:203], v[46:47], off offset:2064
	global_load_dwordx4 v[204:207], v[48:49], off
	global_load_dwordx4 v[208:211], v[48:49], off offset:16
	global_load_dwordx4 v[212:215], v[48:49], off offset:2048
	global_load_dwordx4 v[216:219], v[48:49], off offset:2064
	global_load_dwordx4 v[220:223], v[50:51], off
	global_load_dwordx4 v[224:227], v[50:51], off offset:16
	global_load_dwordx4 v[228:231], v[50:51], off offset:2048
	global_load_dwordx4 v[232:235], v[50:51], off offset:2064
	ds_read_b128 v[72:75], v1 offset:32768
	ds_read_b128 v[76:79], v1 offset:32784
	v_lshlrev_b32_e32 v58, 16, v28
	v_and_b32_e32 v59, 0xffff0000, v28
	v_lshlrev_b32_e32 v62, 16, v29
	v_and_b32_e32 v63, 0xffff0000, v29
	ds_read_b128 v[80:83], v1 offset:34816
	s_waitcnt lgkmcnt(1)
	v_pk_mul_f32 v[84:85], v[76:77], v[58:59]
	v_pk_mul_f32 v[86:87], v[78:79], v[62:63]
	ds_read_b128 v[76:79], v1 offset:34832
	v_lshlrev_b32_e32 v56, 16, v26
	v_and_b32_e32 v57, 0xffff0000, v26
	v_lshlrev_b32_e32 v60, 16, v27
	v_and_b32_e32 v61, 0xffff0000, v27
	s_waitcnt vmcnt(36)
	v_lshlrev_b32_e32 v26, 16, v30
	v_and_b32_e32 v27, 0xffff0000, v30
	v_lshlrev_b32_e32 v28, 16, v31
	v_and_b32_e32 v29, 0xffff0000, v31
	v_pk_fma_f32 v[74:75], v[74:75], v[60:61], v[86:87]
	v_pk_fma_f32 v[72:73], v[72:73], v[56:57], v[84:85]
	v_lshlrev_b32_e32 v30, 16, v32
	v_and_b32_e32 v31, 0xffff0000, v32
	v_lshlrev_b32_e32 v32, 16, v33
	v_and_b32_e32 v33, 0xffff0000, v33
	s_waitcnt lgkmcnt(1)
	v_pk_fma_f32 v[72:73], v[80:81], v[26:27], v[72:73]
	v_pk_fma_f32 v[74:75], v[82:83], v[28:29], v[74:75]
	s_waitcnt lgkmcnt(0)
	v_pk_fma_f32 v[72:73], v[76:77], v[30:31], v[72:73]
	v_pk_fma_f32 v[74:75], v[78:79], v[32:33], v[74:75]
	v_add_f32_e32 v72, v72, v73
	v_add_f32_e32 v73, v74, v75
	v_add_f32_e32 v72, v72, v73
	s_add_u32 s38, s28, s0
	s_addc_u32 s39, s29, s1
	v_add_f32_dpp v72, v72, v72 quad_perm:[1,0,3,2] row_mask:0xf bank_mask:0xf bound_ctrl:1
	s_nop 1
	v_add_f32_dpp v72, v72, v72 quad_perm:[2,3,0,1] row_mask:0xf bank_mask:0xf bound_ctrl:1
	ds_swizzle_b32 v73, v72 offset:swizzle(SWAP,4)
	s_waitcnt lgkmcnt(0)
	v_add_f32_e32 v72, v72, v73
	s_nop 1
	v_add_f32_dpp v72, v72, v72 row_ror:8 row_mask:0xf bank_mask:0xf bound_ctrl:1
	ds_swizzle_b32 v73, v72 offset:swizzle(SWAP,16)
	s_waitcnt lgkmcnt(0)
	v_add_f32_e32 v72, v72, v73
	v_mov_b32_e32 v73, v72
	v_mov_b32_e32 v74, v72
	s_nop 1
	v_permlane32_swap_b32_e32 v73, v74
	s_and_saveexec_b64 s[34:35], s[4:5]
	s_cbranch_execz .LBB0_155
	v_cndmask_b32_e64 v73, v73, v74, s[2:3]
	v_add_f32_e32 v72, v72, v73
	global_store_dword v64, v72, s[38:39]
.LBB0_155:
	s_or_b64 exec, exec, s[34:35]
	v_add_co_u32_e32 v92, vcc, s13, v54
	s_waitcnt vmcnt(0)
	v_pk_add_f32 v[74:75], v[110:111], 1.0 op_sel_hi:[1,0]
	v_pk_add_f32 v[72:73], v[108:109], 1.0 op_sel_hi:[1,0]
	v_pk_add_f32 v[78:79], v[114:115], 1.0 op_sel_hi:[1,0]
	v_pk_add_f32 v[76:77], v[112:113], 1.0 op_sel_hi:[1,0]
	v_pk_mul_f32 v[74:75], v[24:25], v[74:75]
	v_pk_mul_f32 v[72:73], v[22:23], v[72:73]
	v_addc_co_u32_e32 v93, vcc, 0, v55, vcc
	v_pk_mul_f32 v[78:79], v[20:21], v[78:79]
	v_pk_mul_f32 v[76:77], v[18:19], v[76:77]
	v_pk_mul_f32 v[74:75], v[74:75], v[60:61]
	v_pk_mul_f32 v[72:73], v[72:73], v[56:57]
	v_pk_mul_f32 v[78:79], v[78:79], v[62:63]
	v_pk_mul_f32 v[76:77], v[76:77], v[58:59]
	v_cvt_pk_bf16_f32 v72, v72, v73
	v_cvt_pk_bf16_f32 v73, v74, v75
	s_nop 0
	v_cvt_pk_bf16_f32 v74, v76, v77
	v_cvt_pk_bf16_f32 v75, v78, v79
	global_store_dwordx4 v[92:93], v[72:75], off
	s_nop 1
	s_nop 0
	v_pk_add_f32 v[74:75], v[118:119], 1.0 op_sel_hi:[1,0]
	v_pk_add_f32 v[72:73], v[116:117], 1.0 op_sel_hi:[1,0]
	v_pk_add_f32 v[78:79], v[122:123], 1.0 op_sel_hi:[1,0]
	v_pk_add_f32 v[76:77], v[120:121], 1.0 op_sel_hi:[1,0]
	v_pk_mul_f32 v[74:75], v[16:17], v[74:75]
	v_pk_mul_f32 v[72:73], v[14:15], v[72:73]
	v_pk_mul_f32 v[78:79], v[12:13], v[78:79]
	v_pk_mul_f32 v[76:77], v[10:11], v[76:77]
	v_pk_mul_f32 v[74:75], v[74:75], v[28:29]
	v_pk_mul_f32 v[72:73], v[72:73], v[26:27]
	v_pk_mul_f32 v[78:79], v[78:79], v[32:33]
	v_pk_mul_f32 v[76:77], v[76:77], v[30:31]
	v_cvt_pk_bf16_f32 v72, v72, v73
	v_cvt_pk_bf16_f32 v73, v74, v75
	s_nop 0
	v_cvt_pk_bf16_f32 v74, v76, v77
	v_cvt_pk_bf16_f32 v75, v78, v79
	ds_read_b128 v[76:79], v1 offset:36880
	ds_read_b128 v[80:83], v1 offset:36864
	ds_read_b128 v[84:87], v1 offset:38912
	ds_read_b128 v[88:91], v1 offset:38928
	global_store_dwordx4 v[92:93], v[72:75], off offset:1024
	s_nop 1
	s_waitcnt lgkmcnt(3)
	v_pk_mul_f32 v[78:79], v[78:79], v[62:63]
	v_pk_mul_f32 v[76:77], v[76:77], v[58:59]
	s_waitcnt lgkmcnt(2)
	v_pk_fma_f32 v[78:79], v[82:83], v[60:61], v[78:79]
	v_pk_fma_f32 v[76:77], v[80:81], v[56:57], v[76:77]
	s_waitcnt lgkmcnt(1)
	v_pk_fma_f32 v[78:79], v[86:87], v[28:29], v[78:79]
	v_pk_fma_f32 v[76:77], v[84:85], v[26:27], v[76:77]
	s_waitcnt lgkmcnt(0)
	v_pk_fma_f32 v[78:79], v[90:91], v[32:33], v[78:79]
	v_pk_fma_f32 v[76:77], v[88:89], v[30:31], v[76:77]
	s_nop 0
	v_add_f32_e32 v76, v76, v77
	v_add_f32_e32 v77, v78, v79
	v_add_f32_e32 v76, v76, v77
	s_nop 1
	v_add_f32_dpp v76, v76, v76 quad_perm:[1,0,3,2] row_mask:0xf bank_mask:0xf bound_ctrl:1
	s_nop 1
	v_add_f32_dpp v76, v76, v76 quad_perm:[2,3,0,1] row_mask:0xf bank_mask:0xf bound_ctrl:1
	ds_swizzle_b32 v77, v76 offset:swizzle(SWAP,4)
	s_waitcnt lgkmcnt(0)
	v_add_f32_e32 v76, v76, v77
	s_nop 1
	v_add_f32_dpp v76, v76, v76 row_ror:8 row_mask:0xf bank_mask:0xf bound_ctrl:1
	ds_swizzle_b32 v77, v76 offset:swizzle(SWAP,16)
	s_waitcnt lgkmcnt(0)
	v_add_f32_e32 v72, v76, v77
	v_mov_b32_e32 v73, v72
	v_mov_b32_e32 v74, v72
	s_nop 1
	v_permlane32_swap_b32_e32 v73, v74
	s_and_saveexec_b64 s[34:35], s[4:5]
	s_cbranch_execz .LBB0_157
	v_cndmask_b32_e64 v73, v73, v74, s[2:3]
	v_add_f32_e32 v72, v72, v73
	global_store_dword v65, v72, s[38:39]
.LBB0_157:
	s_or_b64 exec, exec, s[34:35]
	v_add_co_u32_e32 v92, vcc, s17, v54
	v_pk_add_f32 v[74:75], v[126:127], 1.0 op_sel_hi:[1,0]
	v_pk_add_f32 v[72:73], v[124:125], 1.0 op_sel_hi:[1,0]
	v_pk_add_f32 v[78:79], v[130:131], 1.0 op_sel_hi:[1,0]
	v_pk_add_f32 v[76:77], v[128:129], 1.0 op_sel_hi:[1,0]
	v_pk_mul_f32 v[74:75], v[24:25], v[74:75]
	v_pk_mul_f32 v[72:73], v[22:23], v[72:73]
	v_addc_co_u32_e32 v93, vcc, 0, v55, vcc
	v_pk_mul_f32 v[78:79], v[20:21], v[78:79]
	v_pk_mul_f32 v[76:77], v[18:19], v[76:77]
	v_pk_mul_f32 v[74:75], v[74:75], v[60:61]
	v_pk_mul_f32 v[72:73], v[72:73], v[56:57]
	v_pk_mul_f32 v[78:79], v[78:79], v[62:63]
	v_pk_mul_f32 v[76:77], v[76:77], v[58:59]
	v_cvt_pk_bf16_f32 v72, v72, v73
	v_cvt_pk_bf16_f32 v73, v74, v75
	s_nop 0
	v_cvt_pk_bf16_f32 v74, v76, v77
	v_cvt_pk_bf16_f32 v75, v78, v79
	global_store_dwordx4 v[92:93], v[72:75], off
	s_nop 1
	s_nop 0
	v_pk_add_f32 v[74:75], v[134:135], 1.0 op_sel_hi:[1,0]
	v_pk_add_f32 v[72:73], v[132:133], 1.0 op_sel_hi:[1,0]
	v_pk_add_f32 v[78:79], v[138:139], 1.0 op_sel_hi:[1,0]
	v_pk_add_f32 v[76:77], v[136:137], 1.0 op_sel_hi:[1,0]
	v_pk_mul_f32 v[74:75], v[16:17], v[74:75]
	v_pk_mul_f32 v[72:73], v[14:15], v[72:73]
	v_pk_mul_f32 v[78:79], v[12:13], v[78:79]
	v_pk_mul_f32 v[76:77], v[10:11], v[76:77]
	v_pk_mul_f32 v[74:75], v[74:75], v[28:29]
	v_pk_mul_f32 v[72:73], v[72:73], v[26:27]
	v_pk_mul_f32 v[78:79], v[78:79], v[32:33]
	v_pk_mul_f32 v[76:77], v[76:77], v[30:31]
	v_cvt_pk_bf16_f32 v72, v72, v73
	v_cvt_pk_bf16_f32 v73, v74, v75
	s_nop 0
	v_cvt_pk_bf16_f32 v74, v76, v77
	v_cvt_pk_bf16_f32 v75, v78, v79
	ds_read_b128 v[76:79], v1 offset:40976
	ds_read_b128 v[80:83], v1 offset:40960
	ds_read_b128 v[84:87], v1 offset:43008
	ds_read_b128 v[88:91], v1 offset:43024
	global_store_dwordx4 v[92:93], v[72:75], off offset:1024
	s_nop 1
	s_waitcnt lgkmcnt(3)
	v_pk_mul_f32 v[78:79], v[78:79], v[62:63]
	v_pk_mul_f32 v[76:77], v[76:77], v[58:59]
	s_waitcnt lgkmcnt(2)
	v_pk_fma_f32 v[78:79], v[82:83], v[60:61], v[78:79]
	v_pk_fma_f32 v[76:77], v[80:81], v[56:57], v[76:77]
	s_waitcnt lgkmcnt(1)
	v_pk_fma_f32 v[78:79], v[86:87], v[28:29], v[78:79]
	v_pk_fma_f32 v[76:77], v[84:85], v[26:27], v[76:77]
	s_waitcnt lgkmcnt(0)
	v_pk_fma_f32 v[78:79], v[90:91], v[32:33], v[78:79]
	v_pk_fma_f32 v[76:77], v[88:89], v[30:31], v[76:77]
	s_nop 0
	v_add_f32_e32 v76, v76, v77
	v_add_f32_e32 v77, v78, v79
	v_add_f32_e32 v76, v76, v77
	s_nop 1
	v_add_f32_dpp v76, v76, v76 quad_perm:[1,0,3,2] row_mask:0xf bank_mask:0xf bound_ctrl:1
	s_nop 1
	v_add_f32_dpp v76, v76, v76 quad_perm:[2,3,0,1] row_mask:0xf bank_mask:0xf bound_ctrl:1
	ds_swizzle_b32 v77, v76 offset:swizzle(SWAP,4)
	s_waitcnt lgkmcnt(0)
	v_add_f32_e32 v76, v76, v77
	s_nop 1
	v_add_f32_dpp v76, v76, v76 row_ror:8 row_mask:0xf bank_mask:0xf bound_ctrl:1
	ds_swizzle_b32 v77, v76 offset:swizzle(SWAP,16)
	s_waitcnt lgkmcnt(0)
	v_add_f32_e32 v72, v76, v77
	v_mov_b32_e32 v73, v72
	v_mov_b32_e32 v74, v72
	s_nop 1
	v_permlane32_swap_b32_e32 v73, v74
	s_and_saveexec_b64 s[34:35], s[4:5]
	s_cbranch_execz .LBB0_159
	v_cndmask_b32_e64 v73, v73, v74, s[2:3]
	v_add_f32_e32 v72, v72, v73
	global_store_dword v66, v72, s[38:39]
.LBB0_159:
	s_or_b64 exec, exec, s[34:35]
	v_add_co_u32_e32 v92, vcc, s21, v54
	v_pk_add_f32 v[74:75], v[142:143], 1.0 op_sel_hi:[1,0]
	v_pk_add_f32 v[72:73], v[140:141], 1.0 op_sel_hi:[1,0]
	v_pk_add_f32 v[78:79], v[146:147], 1.0 op_sel_hi:[1,0]
	v_pk_add_f32 v[76:77], v[144:145], 1.0 op_sel_hi:[1,0]
	v_pk_mul_f32 v[74:75], v[24:25], v[74:75]
	v_pk_mul_f32 v[72:73], v[22:23], v[72:73]
	v_addc_co_u32_e32 v93, vcc, 0, v55, vcc
	v_pk_mul_f32 v[78:79], v[20:21], v[78:79]
	v_pk_mul_f32 v[76:77], v[18:19], v[76:77]
	v_pk_mul_f32 v[74:75], v[74:75], v[60:61]
	v_pk_mul_f32 v[72:73], v[72:73], v[56:57]
	v_pk_mul_f32 v[78:79], v[78:79], v[62:63]
	v_pk_mul_f32 v[76:77], v[76:77], v[58:59]
	v_cvt_pk_bf16_f32 v72, v72, v73
	v_cvt_pk_bf16_f32 v73, v74, v75
	s_nop 0
	v_cvt_pk_bf16_f32 v74, v76, v77
	v_cvt_pk_bf16_f32 v75, v78, v79
	global_store_dwordx4 v[92:93], v[72:75], off
	s_nop 1
	s_nop 0
	v_pk_add_f32 v[74:75], v[150:151], 1.0 op_sel_hi:[1,0]
	v_pk_add_f32 v[72:73], v[148:149], 1.0 op_sel_hi:[1,0]
	v_pk_add_f32 v[78:79], v[154:155], 1.0 op_sel_hi:[1,0]
	v_pk_add_f32 v[76:77], v[152:153], 1.0 op_sel_hi:[1,0]
	v_pk_mul_f32 v[74:75], v[16:17], v[74:75]
	v_pk_mul_f32 v[72:73], v[14:15], v[72:73]
	v_pk_mul_f32 v[78:79], v[12:13], v[78:79]
	v_pk_mul_f32 v[76:77], v[10:11], v[76:77]
	v_pk_mul_f32 v[74:75], v[74:75], v[28:29]
	v_pk_mul_f32 v[72:73], v[72:73], v[26:27]
	v_pk_mul_f32 v[78:79], v[78:79], v[32:33]
	v_pk_mul_f32 v[76:77], v[76:77], v[30:31]
	v_cvt_pk_bf16_f32 v72, v72, v73
	v_cvt_pk_bf16_f32 v73, v74, v75
	s_nop 0
	v_cvt_pk_bf16_f32 v74, v76, v77
	v_cvt_pk_bf16_f32 v75, v78, v79
	ds_read_b128 v[76:79], v1 offset:45072
	ds_read_b128 v[80:83], v1 offset:45056
	ds_read_b128 v[84:87], v1 offset:47104
	ds_read_b128 v[88:91], v1 offset:47120
	global_store_dwordx4 v[92:93], v[72:75], off offset:1024
	s_nop 1
	s_waitcnt lgkmcnt(3)
	v_pk_mul_f32 v[78:79], v[78:79], v[62:63]
	v_pk_mul_f32 v[76:77], v[76:77], v[58:59]
	s_waitcnt lgkmcnt(2)
	v_pk_fma_f32 v[78:79], v[82:83], v[60:61], v[78:79]
	v_pk_fma_f32 v[76:77], v[80:81], v[56:57], v[76:77]
	s_waitcnt lgkmcnt(1)
	v_pk_fma_f32 v[78:79], v[86:87], v[28:29], v[78:79]
	v_pk_fma_f32 v[76:77], v[84:85], v[26:27], v[76:77]
	s_waitcnt lgkmcnt(0)
	v_pk_fma_f32 v[78:79], v[90:91], v[32:33], v[78:79]
	v_pk_fma_f32 v[76:77], v[88:89], v[30:31], v[76:77]
	s_nop 0
	v_add_f32_e32 v76, v76, v77
	v_add_f32_e32 v77, v78, v79
	v_add_f32_e32 v76, v76, v77
	s_nop 1
	v_add_f32_dpp v76, v76, v76 quad_perm:[1,0,3,2] row_mask:0xf bank_mask:0xf bound_ctrl:1
	s_nop 1
	v_add_f32_dpp v76, v76, v76 quad_perm:[2,3,0,1] row_mask:0xf bank_mask:0xf bound_ctrl:1
	ds_swizzle_b32 v77, v76 offset:swizzle(SWAP,4)
	s_waitcnt lgkmcnt(0)
	v_add_f32_e32 v76, v76, v77
	s_nop 1
	v_add_f32_dpp v76, v76, v76 row_ror:8 row_mask:0xf bank_mask:0xf bound_ctrl:1
	ds_swizzle_b32 v77, v76 offset:swizzle(SWAP,16)
	s_waitcnt lgkmcnt(0)
	v_add_f32_e32 v72, v76, v77
	v_mov_b32_e32 v73, v72
	v_mov_b32_e32 v74, v72
	s_nop 1
	v_permlane32_swap_b32_e32 v73, v74
	s_and_saveexec_b64 s[34:35], s[4:5]
	s_cbranch_execz .LBB0_161
	v_cndmask_b32_e64 v73, v73, v74, s[2:3]
	v_add_f32_e32 v72, v72, v73
	global_store_dword v67, v72, s[38:39]
.LBB0_161:
	s_or_b64 exec, exec, s[34:35]
	v_add_co_u32_e32 v92, vcc, s33, v54
	v_pk_add_f32 v[74:75], v[158:159], 1.0 op_sel_hi:[1,0]
	v_pk_add_f32 v[72:73], v[156:157], 1.0 op_sel_hi:[1,0]
	v_pk_add_f32 v[78:79], v[162:163], 1.0 op_sel_hi:[1,0]
	v_pk_add_f32 v[76:77], v[160:161], 1.0 op_sel_hi:[1,0]
	v_pk_mul_f32 v[74:75], v[24:25], v[74:75]
	v_pk_mul_f32 v[72:73], v[22:23], v[72:73]
	v_addc_co_u32_e32 v93, vcc, 0, v55, vcc
	v_pk_mul_f32 v[78:79], v[20:21], v[78:79]
	v_pk_mul_f32 v[76:77], v[18:19], v[76:77]
	v_pk_mul_f32 v[74:75], v[74:75], v[60:61]
	v_pk_mul_f32 v[72:73], v[72:73], v[56:57]
	v_pk_mul_f32 v[78:79], v[78:79], v[62:63]
	v_pk_mul_f32 v[76:77], v[76:77], v[58:59]
	v_cvt_pk_bf16_f32 v72, v72, v73
	v_cvt_pk_bf16_f32 v73, v74, v75
	s_nop 0
	v_cvt_pk_bf16_f32 v74, v76, v77
	v_cvt_pk_bf16_f32 v75, v78, v79
	global_store_dwordx4 v[92:93], v[72:75], off
	s_nop 1
	s_nop 0
	v_pk_add_f32 v[74:75], v[166:167], 1.0 op_sel_hi:[1,0]
	v_pk_add_f32 v[72:73], v[164:165], 1.0 op_sel_hi:[1,0]
	v_pk_add_f32 v[78:79], v[170:171], 1.0 op_sel_hi:[1,0]
	v_pk_add_f32 v[76:77], v[168:169], 1.0 op_sel_hi:[1,0]
	v_pk_mul_f32 v[74:75], v[16:17], v[74:75]
	v_pk_mul_f32 v[72:73], v[14:15], v[72:73]
	v_pk_mul_f32 v[78:79], v[12:13], v[78:79]
	v_pk_mul_f32 v[76:77], v[10:11], v[76:77]
	v_pk_mul_f32 v[74:75], v[74:75], v[28:29]
	v_pk_mul_f32 v[72:73], v[72:73], v[26:27]
	v_pk_mul_f32 v[78:79], v[78:79], v[32:33]
	v_pk_mul_f32 v[76:77], v[76:77], v[30:31]
	v_cvt_pk_bf16_f32 v72, v72, v73
	v_cvt_pk_bf16_f32 v73, v74, v75
	s_nop 0
	v_cvt_pk_bf16_f32 v74, v76, v77
	v_cvt_pk_bf16_f32 v75, v78, v79
	ds_read_b128 v[76:79], v1 offset:49168
	ds_read_b128 v[80:83], v1 offset:49152
	ds_read_b128 v[84:87], v1 offset:51200
	ds_read_b128 v[88:91], v1 offset:51216
	global_store_dwordx4 v[92:93], v[72:75], off offset:1024
	s_nop 1
	s_waitcnt lgkmcnt(3)
	v_pk_mul_f32 v[78:79], v[78:79], v[62:63]
	v_pk_mul_f32 v[76:77], v[76:77], v[58:59]
	s_waitcnt lgkmcnt(2)
	v_pk_fma_f32 v[78:79], v[82:83], v[60:61], v[78:79]
	v_pk_fma_f32 v[76:77], v[80:81], v[56:57], v[76:77]
	s_waitcnt lgkmcnt(1)
	v_pk_fma_f32 v[78:79], v[86:87], v[28:29], v[78:79]
	v_pk_fma_f32 v[76:77], v[84:85], v[26:27], v[76:77]
	s_waitcnt lgkmcnt(0)
	v_pk_fma_f32 v[78:79], v[90:91], v[32:33], v[78:79]
	v_pk_fma_f32 v[76:77], v[88:89], v[30:31], v[76:77]
	s_nop 0
	v_add_f32_e32 v76, v76, v77
	v_add_f32_e32 v77, v78, v79
	v_add_f32_e32 v76, v76, v77
	s_nop 1
	v_add_f32_dpp v76, v76, v76 quad_perm:[1,0,3,2] row_mask:0xf bank_mask:0xf bound_ctrl:1
	s_nop 1
	v_add_f32_dpp v76, v76, v76 quad_perm:[2,3,0,1] row_mask:0xf bank_mask:0xf bound_ctrl:1
	ds_swizzle_b32 v77, v76 offset:swizzle(SWAP,4)
	s_waitcnt lgkmcnt(0)
	v_add_f32_e32 v76, v76, v77
	s_nop 1
	v_add_f32_dpp v76, v76, v76 row_ror:8 row_mask:0xf bank_mask:0xf bound_ctrl:1
	ds_swizzle_b32 v77, v76 offset:swizzle(SWAP,16)
	s_waitcnt lgkmcnt(0)
	v_add_f32_e32 v72, v76, v77
	v_mov_b32_e32 v73, v72
	v_mov_b32_e32 v74, v72
	s_nop 1
	v_permlane32_swap_b32_e32 v73, v74
	s_and_saveexec_b64 s[34:35], s[4:5]
	s_cbranch_execz .LBB0_163
	v_cndmask_b32_e64 v73, v73, v74, s[2:3]
	v_add_f32_e32 v72, v72, v73
	global_store_dword v68, v72, s[38:39]
.LBB0_163:
	s_or_b64 exec, exec, s[34:35]
	v_add_co_u32_e32 v92, vcc, s44, v54
	v_pk_add_f32 v[74:75], v[174:175], 1.0 op_sel_hi:[1,0]
	v_pk_add_f32 v[72:73], v[172:173], 1.0 op_sel_hi:[1,0]
	v_pk_add_f32 v[78:79], v[178:179], 1.0 op_sel_hi:[1,0]
	v_pk_add_f32 v[76:77], v[176:177], 1.0 op_sel_hi:[1,0]
	v_pk_mul_f32 v[74:75], v[24:25], v[74:75]
	v_pk_mul_f32 v[72:73], v[22:23], v[72:73]
	v_addc_co_u32_e32 v93, vcc, 0, v55, vcc
	v_pk_mul_f32 v[78:79], v[20:21], v[78:79]
	v_pk_mul_f32 v[76:77], v[18:19], v[76:77]
	v_pk_mul_f32 v[74:75], v[74:75], v[60:61]
	v_pk_mul_f32 v[72:73], v[72:73], v[56:57]
	v_pk_mul_f32 v[78:79], v[78:79], v[62:63]
	v_pk_mul_f32 v[76:77], v[76:77], v[58:59]
	v_cvt_pk_bf16_f32 v72, v72, v73
	v_cvt_pk_bf16_f32 v73, v74, v75
	s_nop 0
	v_cvt_pk_bf16_f32 v74, v76, v77
	v_cvt_pk_bf16_f32 v75, v78, v79
	global_store_dwordx4 v[92:93], v[72:75], off
	s_nop 1
	s_nop 0
	v_pk_add_f32 v[74:75], v[182:183], 1.0 op_sel_hi:[1,0]
	v_pk_add_f32 v[72:73], v[180:181], 1.0 op_sel_hi:[1,0]
	v_pk_add_f32 v[78:79], v[186:187], 1.0 op_sel_hi:[1,0]
	v_pk_add_f32 v[76:77], v[184:185], 1.0 op_sel_hi:[1,0]
	v_pk_mul_f32 v[74:75], v[16:17], v[74:75]
	v_pk_mul_f32 v[72:73], v[14:15], v[72:73]
	v_pk_mul_f32 v[78:79], v[12:13], v[78:79]
	v_pk_mul_f32 v[76:77], v[10:11], v[76:77]
	v_pk_mul_f32 v[74:75], v[74:75], v[28:29]
	v_pk_mul_f32 v[72:73], v[72:73], v[26:27]
	v_pk_mul_f32 v[78:79], v[78:79], v[32:33]
	v_pk_mul_f32 v[76:77], v[76:77], v[30:31]
	v_cvt_pk_bf16_f32 v72, v72, v73
	v_cvt_pk_bf16_f32 v73, v74, v75
	s_nop 0
	v_cvt_pk_bf16_f32 v74, v76, v77
	v_cvt_pk_bf16_f32 v75, v78, v79
	ds_read_b128 v[76:79], v1 offset:53264
	ds_read_b128 v[80:83], v1 offset:53248
	ds_read_b128 v[84:87], v1 offset:55296
	ds_read_b128 v[88:91], v1 offset:55312
	global_store_dwordx4 v[92:93], v[72:75], off offset:1024
	s_nop 1
	s_waitcnt lgkmcnt(3)
	v_pk_mul_f32 v[78:79], v[78:79], v[62:63]
	v_pk_mul_f32 v[76:77], v[76:77], v[58:59]
	s_waitcnt lgkmcnt(2)
	v_pk_fma_f32 v[78:79], v[82:83], v[60:61], v[78:79]
	v_pk_fma_f32 v[76:77], v[80:81], v[56:57], v[76:77]
	s_waitcnt lgkmcnt(1)
	v_pk_fma_f32 v[78:79], v[86:87], v[28:29], v[78:79]
	v_pk_fma_f32 v[76:77], v[84:85], v[26:27], v[76:77]
	s_waitcnt lgkmcnt(0)
	v_pk_fma_f32 v[78:79], v[90:91], v[32:33], v[78:79]
	v_pk_fma_f32 v[76:77], v[88:89], v[30:31], v[76:77]
	s_nop 0
	v_add_f32_e32 v76, v76, v77
	v_add_f32_e32 v77, v78, v79
	v_add_f32_e32 v76, v76, v77
	s_nop 1
	v_add_f32_dpp v76, v76, v76 quad_perm:[1,0,3,2] row_mask:0xf bank_mask:0xf bound_ctrl:1
	s_nop 1
	v_add_f32_dpp v76, v76, v76 quad_perm:[2,3,0,1] row_mask:0xf bank_mask:0xf bound_ctrl:1
	ds_swizzle_b32 v77, v76 offset:swizzle(SWAP,4)
	s_waitcnt lgkmcnt(0)
	v_add_f32_e32 v76, v76, v77
	s_nop 1
	v_add_f32_dpp v76, v76, v76 row_ror:8 row_mask:0xf bank_mask:0xf bound_ctrl:1
	ds_swizzle_b32 v77, v76 offset:swizzle(SWAP,16)
	s_waitcnt lgkmcnt(0)
	v_add_f32_e32 v72, v76, v77
	v_mov_b32_e32 v73, v72
	v_mov_b32_e32 v74, v72
	s_nop 1
	v_permlane32_swap_b32_e32 v73, v74
	s_and_saveexec_b64 s[34:35], s[4:5]
	s_cbranch_execz .LBB0_165
	v_cndmask_b32_e64 v73, v73, v74, s[2:3]
	v_add_f32_e32 v72, v72, v73
	global_store_dword v69, v72, s[38:39]
.LBB0_165:
	s_or_b64 exec, exec, s[34:35]
	v_add_co_u32_e32 v92, vcc, s45, v54
	v_pk_add_f32 v[74:75], v[190:191], 1.0 op_sel_hi:[1,0]
	v_pk_add_f32 v[72:73], v[188:189], 1.0 op_sel_hi:[1,0]
	v_pk_add_f32 v[78:79], v[194:195], 1.0 op_sel_hi:[1,0]
	v_pk_add_f32 v[76:77], v[192:193], 1.0 op_sel_hi:[1,0]
	v_pk_mul_f32 v[74:75], v[24:25], v[74:75]
	v_pk_mul_f32 v[72:73], v[22:23], v[72:73]
	v_addc_co_u32_e32 v93, vcc, 0, v55, vcc
	v_pk_mul_f32 v[78:79], v[20:21], v[78:79]
	v_pk_mul_f32 v[76:77], v[18:19], v[76:77]
	v_pk_mul_f32 v[74:75], v[74:75], v[60:61]
	v_pk_mul_f32 v[72:73], v[72:73], v[56:57]
	v_pk_mul_f32 v[78:79], v[78:79], v[62:63]
	v_pk_mul_f32 v[76:77], v[76:77], v[58:59]
	v_cvt_pk_bf16_f32 v72, v72, v73
	v_cvt_pk_bf16_f32 v73, v74, v75
	s_nop 0
	v_cvt_pk_bf16_f32 v74, v76, v77
	v_cvt_pk_bf16_f32 v75, v78, v79
	global_store_dwordx4 v[92:93], v[72:75], off
	s_nop 1
	s_nop 0
	v_pk_add_f32 v[74:75], v[198:199], 1.0 op_sel_hi:[1,0]
	v_pk_add_f32 v[72:73], v[196:197], 1.0 op_sel_hi:[1,0]
	v_pk_add_f32 v[78:79], v[202:203], 1.0 op_sel_hi:[1,0]
	v_pk_add_f32 v[76:77], v[200:201], 1.0 op_sel_hi:[1,0]
	v_pk_mul_f32 v[74:75], v[16:17], v[74:75]
	v_pk_mul_f32 v[72:73], v[14:15], v[72:73]
	v_pk_mul_f32 v[78:79], v[12:13], v[78:79]
	v_pk_mul_f32 v[76:77], v[10:11], v[76:77]
	v_pk_mul_f32 v[74:75], v[74:75], v[28:29]
	v_pk_mul_f32 v[72:73], v[72:73], v[26:27]
	v_pk_mul_f32 v[78:79], v[78:79], v[32:33]
	v_pk_mul_f32 v[76:77], v[76:77], v[30:31]
	v_cvt_pk_bf16_f32 v72, v72, v73
	v_cvt_pk_bf16_f32 v73, v74, v75
	s_nop 0
	v_cvt_pk_bf16_f32 v74, v76, v77
	v_cvt_pk_bf16_f32 v75, v78, v79
	ds_read_b128 v[76:79], v1 offset:57360
	ds_read_b128 v[80:83], v1 offset:57344
	ds_read_b128 v[84:87], v1 offset:59392
	ds_read_b128 v[88:91], v1 offset:59408
	global_store_dwordx4 v[92:93], v[72:75], off offset:1024
	s_nop 1
	s_waitcnt lgkmcnt(3)
	v_pk_mul_f32 v[78:79], v[78:79], v[62:63]
	v_pk_mul_f32 v[76:77], v[76:77], v[58:59]
	s_waitcnt lgkmcnt(2)
	v_pk_fma_f32 v[78:79], v[82:83], v[60:61], v[78:79]
	v_pk_fma_f32 v[76:77], v[80:81], v[56:57], v[76:77]
	s_waitcnt lgkmcnt(1)
	v_pk_fma_f32 v[78:79], v[86:87], v[28:29], v[78:79]
	v_pk_fma_f32 v[76:77], v[84:85], v[26:27], v[76:77]
	s_waitcnt lgkmcnt(0)
	v_pk_fma_f32 v[78:79], v[90:91], v[32:33], v[78:79]
	v_pk_fma_f32 v[76:77], v[88:89], v[30:31], v[76:77]
	s_nop 0
	v_add_f32_e32 v76, v76, v77
	v_add_f32_e32 v77, v78, v79
	v_add_f32_e32 v76, v76, v77
	s_nop 1
	v_add_f32_dpp v76, v76, v76 quad_perm:[1,0,3,2] row_mask:0xf bank_mask:0xf bound_ctrl:1
	s_nop 1
	v_add_f32_dpp v76, v76, v76 quad_perm:[2,3,0,1] row_mask:0xf bank_mask:0xf bound_ctrl:1
	ds_swizzle_b32 v77, v76 offset:swizzle(SWAP,4)
	s_waitcnt lgkmcnt(0)
	v_add_f32_e32 v76, v76, v77
	s_nop 1
	v_add_f32_dpp v76, v76, v76 row_ror:8 row_mask:0xf bank_mask:0xf bound_ctrl:1
	ds_swizzle_b32 v77, v76 offset:swizzle(SWAP,16)
	s_waitcnt lgkmcnt(0)
	v_add_f32_e32 v72, v76, v77
	v_mov_b32_e32 v73, v72
	v_mov_b32_e32 v74, v72
	s_nop 1
	v_permlane32_swap_b32_e32 v73, v74
	s_and_saveexec_b64 s[34:35], s[4:5]
	s_cbranch_execz .LBB0_167
	v_cndmask_b32_e64 v73, v73, v74, s[2:3]
	v_add_f32_e32 v72, v72, v73
	global_store_dword v70, v72, s[38:39]
.LBB0_167:
	s_or_b64 exec, exec, s[34:35]
	v_add_co_u32_e32 v92, vcc, s48, v54
	v_pk_add_f32 v[74:75], v[206:207], 1.0 op_sel_hi:[1,0]
	v_pk_add_f32 v[72:73], v[204:205], 1.0 op_sel_hi:[1,0]
	v_pk_add_f32 v[78:79], v[210:211], 1.0 op_sel_hi:[1,0]
	v_pk_add_f32 v[76:77], v[208:209], 1.0 op_sel_hi:[1,0]
	v_pk_mul_f32 v[74:75], v[24:25], v[74:75]
	v_pk_mul_f32 v[72:73], v[22:23], v[72:73]
	v_addc_co_u32_e32 v93, vcc, 0, v55, vcc
	v_pk_mul_f32 v[78:79], v[20:21], v[78:79]
	v_pk_mul_f32 v[76:77], v[18:19], v[76:77]
	v_pk_mul_f32 v[74:75], v[74:75], v[60:61]
	v_pk_mul_f32 v[72:73], v[72:73], v[56:57]
	v_pk_mul_f32 v[78:79], v[78:79], v[62:63]
	v_pk_mul_f32 v[76:77], v[76:77], v[58:59]
	v_cvt_pk_bf16_f32 v72, v72, v73
	v_cvt_pk_bf16_f32 v73, v74, v75
	s_nop 0
	v_cvt_pk_bf16_f32 v74, v76, v77
	v_cvt_pk_bf16_f32 v75, v78, v79
	global_store_dwordx4 v[92:93], v[72:75], off
	s_nop 1
	s_nop 0
	v_pk_add_f32 v[74:75], v[214:215], 1.0 op_sel_hi:[1,0]
	v_pk_add_f32 v[72:73], v[212:213], 1.0 op_sel_hi:[1,0]
	v_pk_add_f32 v[78:79], v[218:219], 1.0 op_sel_hi:[1,0]
	v_pk_add_f32 v[76:77], v[216:217], 1.0 op_sel_hi:[1,0]
	v_pk_mul_f32 v[74:75], v[16:17], v[74:75]
	v_pk_mul_f32 v[72:73], v[14:15], v[72:73]
	v_pk_mul_f32 v[78:79], v[12:13], v[78:79]
	v_pk_mul_f32 v[76:77], v[10:11], v[76:77]
	v_pk_mul_f32 v[74:75], v[74:75], v[28:29]
	v_pk_mul_f32 v[72:73], v[72:73], v[26:27]
	v_pk_mul_f32 v[78:79], v[78:79], v[32:33]
	v_pk_mul_f32 v[76:77], v[76:77], v[30:31]
	v_cvt_pk_bf16_f32 v72, v72, v73
	v_cvt_pk_bf16_f32 v73, v74, v75
	s_nop 0
	v_cvt_pk_bf16_f32 v74, v76, v77
	v_cvt_pk_bf16_f32 v75, v78, v79
	ds_read_b128 v[76:79], v1 offset:61456
	ds_read_b128 v[80:83], v1 offset:61440
	ds_read_b128 v[84:87], v1 offset:63488
	ds_read_b128 v[88:91], v1 offset:63504
	global_store_dwordx4 v[92:93], v[72:75], off offset:1024
	s_nop 1
	s_waitcnt lgkmcnt(3)
	v_pk_mul_f32 v[78:79], v[78:79], v[62:63]
	v_pk_mul_f32 v[76:77], v[76:77], v[58:59]
	s_waitcnt lgkmcnt(2)
	v_pk_fma_f32 v[78:79], v[82:83], v[60:61], v[78:79]
	v_pk_fma_f32 v[76:77], v[80:81], v[56:57], v[76:77]
	s_waitcnt lgkmcnt(1)
	v_pk_fma_f32 v[78:79], v[86:87], v[28:29], v[78:79]
	v_pk_fma_f32 v[76:77], v[84:85], v[26:27], v[76:77]
	s_waitcnt lgkmcnt(0)
	v_pk_fma_f32 v[78:79], v[90:91], v[32:33], v[78:79]
	v_pk_fma_f32 v[76:77], v[88:89], v[30:31], v[76:77]
	s_nop 0
	v_add_f32_e32 v76, v76, v77
	v_add_f32_e32 v77, v78, v79
	v_add_f32_e32 v76, v76, v77
	s_nop 1
	v_add_f32_dpp v76, v76, v76 quad_perm:[1,0,3,2] row_mask:0xf bank_mask:0xf bound_ctrl:1
	s_nop 1
	v_add_f32_dpp v76, v76, v76 quad_perm:[2,3,0,1] row_mask:0xf bank_mask:0xf bound_ctrl:1
	ds_swizzle_b32 v77, v76 offset:swizzle(SWAP,4)
	s_waitcnt lgkmcnt(0)
	v_add_f32_e32 v76, v76, v77
	s_nop 1
	v_add_f32_dpp v76, v76, v76 row_ror:8 row_mask:0xf bank_mask:0xf bound_ctrl:1
	ds_swizzle_b32 v77, v76 offset:swizzle(SWAP,16)
	s_waitcnt lgkmcnt(0)
	v_add_f32_e32 v72, v76, v77
	v_mov_b32_e32 v73, v72
	v_mov_b32_e32 v74, v72
	s_nop 1
	v_permlane32_swap_b32_e32 v73, v74
	s_and_saveexec_b64 s[34:35], s[4:5]
	s_cbranch_execz .LBB0_148
	v_cndmask_b32_e64 v73, v73, v74, s[2:3]
	v_add_f32_e32 v72, v72, v73
	global_store_dword v71, v72, s[38:39]
	s_branch .LBB0_148
